# attention loop: next-tile row-max tree moved into the PV MFMA shadow (max3 chains, no canonicalize ops), row-sum adds trimmed 20->16
# speedup vs baseline: 1.0230x; 1.0183x over previous
.LBB0_883:
	ds_read_b128 v[60:63], v201
	ds_read_b128 v[64:67], v201 offset:1024
	ds_read_b128 v[76:79], v201 offset:3072
	ds_read_b128 v[80:83], v201 offset:2048
	ds_read_b128 v[88:91], v201 offset:6144
	ds_read_b128 v[152:155], v201 offset:7168
	ds_read_b128 v[184:187], v201 offset:9216
	ds_read_b128 v[188:191], v201 offset:8192
	s_waitcnt lgkmcnt(7)
	v_mfma_f32_16x16x32_bf16 v[68:71], v[60:63], v[12:15], v[44:47]
	v_mfma_f32_16x16x32_bf16 v[60:63], v[60:63], v[16:19], v[48:51]
	s_waitcnt lgkmcnt(5)
	v_mfma_f32_16x16x32_bf16 v[84:87], v[76:79], v[12:15], v[44:47]
	v_mfma_f32_16x16x32_bf16 v[76:79], v[76:79], v[16:19], v[48:51]
	v_mfma_f32_16x16x32_bf16 v[68:71], v[64:67], v[4:7], v[68:71]
	v_mfma_f32_16x16x32_bf16 v[60:63], v[64:67], v[20:23], v[60:63]
	ds_read_b128 v[64:67], v201 offset:4096
	ds_read_b128 v[204:207], v201 offset:5120
	s_waitcnt lgkmcnt(5)
	v_mfma_f32_16x16x32_bf16 v[180:183], v[88:91], v[12:15], v[44:47]
	v_mfma_f32_16x16x32_bf16 v[88:91], v[88:91], v[16:19], v[48:51]
	s_waitcnt lgkmcnt(3)
	v_mfma_f32_16x16x32_bf16 v[192:195], v[184:187], v[12:15], v[44:47]
	s_waitcnt lgkmcnt(1)
	v_mfma_f32_16x16x32_bf16 v[208:211], v[64:67], v[4:7], v[84:87]
	v_mfma_f32_16x16x32_bf16 v[64:67], v[64:67], v[20:23], v[76:79]
	s_nop 2
	ds_read_b128 v[76:79], v201 offset:10240
	ds_read_b128 v[216:219], v201 offset:11264
	v_mfma_f32_16x16x32_bf16 v[184:187], v[184:187], v[16:19], v[48:51]
	v_mfma_f32_16x16x32_bf16 v[180:183], v[152:155], v[4:7], v[180:183]
	v_mfma_f32_16x16x32_bf16 v[212:215], v[152:155], v[20:23], v[88:91]
	v_exp_f32_e32 v153, v72
	v_exp_f32_e32 v152, v116
	v_exp_f32_e32 v155, v73
	s_waitcnt lgkmcnt(1)
	v_mfma_f32_16x16x32_bf16 v[192:195], v[76:79], v[4:7], v[192:195]
	v_exp_f32_e32 v154, v117
	s_nop 0
	v_cvt_pk_bf16_f32 v116, v152, v154
	v_mfma_f32_16x16x32_bf16 v[220:223], v[76:79], v[20:23], v[184:187]
	v_mfma_f32_16x16x32_bf16 v[84:87], v[80:83], v[8:11], v[68:71]
	s_nop 1
	v_exp_f32_e32 v187, v111
	v_exp_f32_e32 v185, v75
	v_exp_f32_e32 v184, v119
	v_mfma_f32_16x16x32_bf16 v[88:91], v[80:83], v[24:27], v[60:63]
	v_exp_f32_e32 v186, v115
	v_mfma_f32_16x16x32_bf16 v[80:83], v[204:207], v[24:27], v[64:67]
	v_mfma_f32_16x16x32_bf16 v[60:63], v[188:191], v[8:11], v[180:183]
	v_mfma_f32_16x16x32_bf16 v[68:71], v[188:191], v[24:27], v[212:215]
	v_exp_f32_e32 v191, v109
	v_exp_f32_e32 v189, v110
	v_exp_f32_e32 v181, v74
	s_waitcnt lgkmcnt(0)
	v_mfma_f32_16x16x32_bf16 v[64:67], v[216:219], v[8:11], v[192:195]
	v_exp_f32_e32 v180, v118
	v_exp_f32_e32 v190, v113
	v_exp_f32_e32 v188, v114
	v_exp_f32_e32 v193, v108
	ds_read_b128 v[108:111], v200 offset:32768
	v_exp_f32_e32 v192, v112
	v_mfma_f32_16x16x32_bf16 v[76:79], v[204:207], v[8:11], v[208:211]
	ds_read_b128 v[204:207], v200 offset:34816
	s_nop 1
	ds_read_b128 v[208:211], v200 offset:33792
	v_cvt_pk_bf16_f32 v112, v153, v155
	v_cvt_pk_bf16_f32 v113, v181, v185
	v_cvt_pk_bf16_f32 v114, v193, v191
	v_cvt_pk_bf16_f32 v115, v189, v187
	v_cvt_pk_bf16_f32 v117, v180, v184
	v_cvt_pk_bf16_f32 v118, v192, v190
	v_cvt_pk_bf16_f32 v119, v188, v186
	v_mfma_f32_16x16x32_bf16 v[72:75], v[216:219], v[24:27], v[220:223]
	v_exp_f32_e32 v183, v100
	v_exp_f32_e32 v182, v104
	v_exp_f32_e32 v195, v101
	s_waitcnt lgkmcnt(2)
	v_mfma_f32_16x16x32_bf16 v[148:151], v[108:111], v[112:115], v[148:151]
	v_exp_f32_e32 v194, v105
	v_cvt_pk_bf16_f32 v228, v183, v195
	v_mfma_f32_16x16x32_bf16 v[108:111], v[108:111], v[116:119], v[144:147]
	s_nop 2
	ds_read_b128 v[144:147], v200 offset:36864
	ds_read_b128 v[212:215], v200 offset:35840
	v_cvt_pk_bf16_f32 v232, v182, v194
	s_waitcnt lgkmcnt(3)
	v_mfma_f32_16x16x32_bf16 v[216:219], v[204:207], v[112:115], v[140:143]
	s_nop 2
	v_exp_f32_e32 v141, v102
	v_exp_f32_e32 v140, v106
	v_exp_f32_e32 v143, v103
	v_mfma_f32_16x16x32_bf16 v[100:103], v[204:207], v[116:119], v[136:139]
	v_exp_f32_e32 v142, v107
	ds_read_b128 v[104:107], v200 offset:38912
	s_nop 0
	ds_read_b128 v[136:139], v200 offset:37888
	ds_read_b128 v[220:223], v200 offset:39936
	s_waitcnt lgkmcnt(4)
	v_mfma_f32_16x16x32_bf16 v[204:207], v[144:147], v[112:115], v[132:135]
	v_cvt_pk_bf16_f32 v229, v141, v143
	v_cvt_pk_bf16_f32 v233, v140, v142
	s_waitcnt vmcnt(3)
	ds_write_b128 v197, v[32:35] offset:12288
	v_exp_f32_e32 v133, v92
	v_exp_f32_e32 v132, v96
	v_exp_f32_e32 v135, v93
	v_mfma_f32_16x16x32_bf16 v[144:147], v[144:147], v[116:119], v[128:131]
	v_exp_f32_e32 v134, v97
	v_cvt_pk_bf16_f32 v230, v133, v135
	s_nop 0
	v_exp_f32_e32 v129, v94
	s_waitcnt lgkmcnt(3)
	v_mfma_f32_16x16x32_bf16 v[224:227], v[104:107], v[112:115], v[124:127]
	v_exp_f32_e32 v128, v98
	v_cvt_pk_bf16_f32 v234, v132, v134
	s_nop 0
	v_exp_f32_e32 v125, v95
	v_exp_f32_e32 v124, v99
	v_mfma_f32_16x16x32_bf16 v[92:95], v[104:107], v[116:119], v[120:123]
	v_cvt_pk_bf16_f32 v231, v129, v125
	v_cvt_pk_bf16_f32 v235, v128, v124
	s_nop 0
	v_mfma_f32_16x16x32_bf16 v[120:123], v[208:211], v[228:231], v[148:151]
	v_mfma_f32_16x16x32_bf16 v[104:107], v[208:211], v[232:235], v[108:111]
	v_mfma_f32_16x16x32_bf16 v[116:119], v[212:215], v[228:231], v[216:219]
	v_mfma_f32_16x16x32_bf16 v[100:103], v[212:215], v[232:235], v[100:103]
	s_waitcnt lgkmcnt(2)
	v_mfma_f32_16x16x32_bf16 v[112:115], v[136:139], v[228:231], v[204:207]
	v_mfma_f32_16x16x32_bf16 v[96:99], v[136:139], v[232:235], v[144:147]
	s_waitcnt lgkmcnt(1)
	v_mfma_f32_16x16x32_bf16 v[108:111], v[220:223], v[228:231], v[224:227]
	v_mfma_f32_16x16x32_bf16 v[92:95], v[220:223], v[232:235], v[92:95]
	s_and_saveexec_b64 s[48:49], s[10:11]
	ds_write_b128 v199, v[36:39] offset:12288
	s_or_b64 exec, exec, s[48:49]
	v_pk_add_f32 v[126:127], v[152:153], 0 op_sel_hi:[1,0]
	v_pk_add_f32 v[130:131], v[154:155], 0 op_sel_hi:[1,0]
	v_pk_add_f32 v[136:137], v[180:181], 0 op_sel_hi:[1,0]
	v_pk_add_f32 v[138:139], v[184:185], 0 op_sel_hi:[1,0]
	v_pk_add_f32 v[126:127], v[192:193], v[126:127]
	v_pk_add_f32 v[130:131], v[190:191], v[130:131]
	v_pk_add_f32 v[136:137], v[188:189], v[136:137]
	v_pk_add_f32 v[138:139], v[186:187], v[138:139]
	v_pk_add_f32 v[126:127], v[182:183], v[126:127]
	v_pk_add_f32 v[130:131], v[194:195], v[130:131]
	v_pk_add_f32 v[136:137], v[140:141], v[136:137]
	v_pk_add_f32 v[138:139], v[142:143], v[138:139]
	v_pk_add_f32 v[126:127], v[132:133], v[126:127]
	v_pk_add_f32 v[130:131], v[134:135], v[130:131]
	v_pk_add_f32 v[128:129], v[128:129], v[136:137]
	v_pk_add_f32 v[124:125], v[124:125], v[138:139]
	v_pk_add_f32 v[126:127], v[126:127], v[130:131]
	v_pk_add_f32 v[124:125], v[128:129], v[124:125]
	s_and_b32 s26, s9, 7
	v_pk_add_f32 v[124:125], v[126:127], v[124:125]
	s_waitcnt vmcnt(2)
	ds_write2_b64 v177, v[40:41], v[42:43] offset1:32
	v_pk_add_f32 v[184:185], v[2:3], v[124:125]
	v_lshl_add_u32 v2, s26, 6, v160
	s_lshl_b32 s26, s26, 7
	v_ashrrev_i32_e32 v3, 31, v2
	s_add_u32 s16, s28, s16
	v_lshlrev_b64 v[2:3], 17, v[2:3]
	s_addc_u32 s17, s29, s17
	v_lshl_add_u64 v[2:3], s[16:17], 0, v[2:3]
	s_lshl_b64 s[16:17], s[14:15], 19
	s_lshl_b64 s[14:15], s[14:15], 23
	s_or_b32 s14, s14, s26
	v_lshl_add_u64 v[180:181], v[170:171], 0, s[16:17]
	v_lshl_add_u64 v[182:183], v[172:173], 0, s[14:15]
	v_max3_f32 v246, v88, v89, v90
	v_max3_f32 v247, v84, v85, v86
	v_max3_f32 v246, v246, v91, v80
	v_max3_f32 v247, v247, v87, v76
	v_max3_f32 v246, v246, v81, v82
	v_max3_f32 v247, v247, v77, v78
	v_max3_f32 v246, v246, v83, v68
	v_max3_f32 v247, v247, v79, v60
	v_max3_f32 v246, v246, v69, v70
	v_max3_f32 v247, v247, v61, v62
	v_max3_f32 v246, v246, v71, v72
	v_max3_f32 v247, v247, v63, v64
	v_max3_f32 v246, v246, v73, v74
	v_max3_f32 v247, v247, v65, v66
	s_mov_b32 s26, 2
	s_waitcnt lgkmcnt(0)
	s_barrier
	s_branch .LBB0_887
.LBB0_886:
	v_pk_add_f32 v[236:237], v[186:187], v[188:189]
	v_pk_add_f32 v[238:239], v[148:149], v[154:155]
	v_pk_add_f32 v[240:241], v[144:145], v[152:153]
	v_pk_add_f32 v[242:243], v[142:143], v[150:151]
	v_pk_add_f32 v[236:237], v[236:237], v[140:141]
	v_pk_add_f32 v[238:239], v[238:239], v[132:133]
	v_pk_add_f32 v[240:241], v[136:137], v[240:241]
	v_pk_add_f32 v[242:243], v[134:135], v[242:243]
	v_pk_add_f32 v[236:237], v[236:237], v[138:139]
	v_pk_add_f32 v[238:239], v[238:239], v[146:147]
	v_pk_add_f32 v[240:241], v[124:125], v[240:241]
	v_pk_add_f32 v[242:243], v[126:127], v[242:243]
	s_add_i32 s26, s26, 2
	v_pk_add_f32 v[240:241], v[240:241], v[242:243]
	v_pk_add_f32 v[236:237], v[236:237], v[238:239]
	v_lshl_add_u64 v[2:3], v[2:3], 0, s[42:43]
	v_pk_add_f32 v[236:237], v[236:237], v[240:241]
	v_lshl_add_u64 v[180:181], v[180:181], 0, s[44:45]
	v_pk_add_f32 v[184:185], v[184:185], v[236:237]
	v_lshl_add_u64 v[182:183], v[182:183], 0, s[46:47]
	s_and_b64 vcc, exec, s[48:49]
	s_waitcnt lgkmcnt(0)
	s_barrier
	s_cbranch_vccnz .LBB0_857

.LBB0_893:
	v_max_f32_e32 v124, v246, v75
	v_max_f32_e32 v125, v247, v67
	v_max_f32_e32 v126, v124, v125
	v_cmp_lt_f32_e32 vcc, s8, v126
	s_cbranch_vccz .LBB0_895
	v_and_b32_e32 v127, 64, v202
	v_xor_b32_e32 v126, 16, v202
	v_add_u32_e32 v127, 64, v127
	v_cmp_lt_i32_e32 vcc, v126, v127
	v_xor_b32_e32 v129, 32, v202
	s_nop 0
	v_cndmask_b32_e32 v126, v202, v126, vcc
	v_lshlrev_b32_e32 v126, 2, v126
	ds_bpermute_b32 v128, v126, v125
	ds_bpermute_b32 v126, v126, v124
	v_cmp_lt_i32_e32 vcc, v129, v127
	v_max_f32_e32 v125, v125, v125
	v_max_f32_e32 v124, v124, v124
	s_waitcnt lgkmcnt(1)
	v_max_f32_e32 v128, v128, v128
	v_cndmask_b32_e32 v127, v202, v129, vcc
	v_max_f32_e32 v125, v125, v128
	v_lshlrev_b32_e32 v127, 2, v127
	s_waitcnt lgkmcnt(0)
	v_max_f32_e32 v126, v126, v126
	ds_bpermute_b32 v128, v127, v125
	v_max_f32_e32 v124, v124, v126
	ds_bpermute_b32 v126, v127, v124
	s_waitcnt lgkmcnt(1)
	v_max_f32_e32 v127, v128, v128
	v_max_f32_e32 v125, v125, v127
	s_waitcnt lgkmcnt(0)
	v_max_f32_e32 v126, v126, v126
	v_max_f32_e32 v124, v124, v126
	v_cmp_lt_f32_e32 vcc, s8, v125
	s_nop 1
	v_cndmask_b32_e32 v125, 0, v125, vcc
	v_cmp_lt_f32_e32 vcc, s8, v124
	v_sub_f32_e32 v84, v84, v125
	v_sub_f32_e32 v85, v85, v125
	v_cndmask_b32_e32 v128, 0, v124, vcc
	v_exp_f32_e64 v124, -v125
	v_exp_f32_e64 v126, -v128
	v_sub_f32_e32 v86, v86, v125
	v_sub_f32_e32 v87, v87, v125
	v_sub_f32_e32 v88, v88, v128
	v_pk_mul_f32 v[106:107], v[106:107], v[126:127] op_sel_hi:[1,0]
	v_pk_mul_f32 v[104:105], v[104:105], v[126:127] op_sel_hi:[1,0]
	v_pk_mul_f32 v[102:103], v[102:103], v[126:127] op_sel_hi:[1,0]
	v_pk_mul_f32 v[100:101], v[100:101], v[126:127] op_sel_hi:[1,0]
	v_pk_mul_f32 v[98:99], v[98:99], v[126:127] op_sel_hi:[1,0]
	v_pk_mul_f32 v[96:97], v[96:97], v[126:127] op_sel_hi:[1,0]
	v_pk_mul_f32 v[94:95], v[94:95], v[126:127] op_sel_hi:[1,0]
	v_pk_mul_f32 v[92:93], v[92:93], v[126:127] op_sel_hi:[1,0]
	v_mov_b32_e32 v127, v124
	v_sub_f32_e32 v89, v89, v128
	v_sub_f32_e32 v90, v90, v128
	v_sub_f32_e32 v91, v91, v128
	v_pk_mul_f32 v[122:123], v[122:123], v[124:125] op_sel_hi:[1,0]
	v_pk_mul_f32 v[120:121], v[120:121], v[124:125] op_sel_hi:[1,0]
	v_sub_f32_e32 v76, v76, v125
	v_sub_f32_e32 v77, v77, v125
	v_sub_f32_e32 v78, v78, v125
	v_sub_f32_e32 v79, v79, v125
	v_sub_f32_e32 v80, v80, v128
	v_sub_f32_e32 v81, v81, v128
	v_sub_f32_e32 v82, v82, v128
	v_sub_f32_e32 v83, v83, v128
	v_pk_mul_f32 v[118:119], v[118:119], v[124:125] op_sel_hi:[1,0]
	v_pk_mul_f32 v[116:117], v[116:117], v[124:125] op_sel_hi:[1,0]
	v_sub_f32_e32 v60, v60, v125
	v_sub_f32_e32 v61, v61, v125
	v_sub_f32_e32 v62, v62, v125
	v_sub_f32_e32 v63, v63, v125
	v_sub_f32_e32 v68, v68, v128
	v_sub_f32_e32 v69, v69, v128
	v_sub_f32_e32 v70, v70, v128
	v_sub_f32_e32 v71, v71, v128
	v_pk_mul_f32 v[114:115], v[114:115], v[124:125] op_sel_hi:[1,0]
	v_pk_mul_f32 v[112:113], v[112:113], v[124:125] op_sel_hi:[1,0]
	v_sub_f32_e32 v64, v64, v125
	v_sub_f32_e32 v65, v65, v125
	v_sub_f32_e32 v66, v66, v125
	v_sub_f32_e32 v67, v67, v125
	v_sub_f32_e32 v72, v72, v128
	v_sub_f32_e32 v73, v73, v128
	v_sub_f32_e32 v74, v74, v128
	v_sub_f32_e32 v75, v75, v128
	v_pk_mul_f32 v[110:111], v[110:111], v[124:125] op_sel_hi:[1,0]
	v_pk_mul_f32 v[108:109], v[108:109], v[124:125] op_sel_hi:[1,0]
	v_pk_mul_f32 v[184:185], v[184:185], v[126:127]
	v_sub_f32_e32 v47, v47, v125
	v_sub_f32_e32 v46, v46, v125
	v_sub_f32_e32 v45, v45, v125
	v_sub_f32_e32 v44, v44, v125
	v_sub_f32_e32 v51, v51, v128
	v_sub_f32_e32 v50, v50, v128
	v_sub_f32_e32 v49, v49, v128
	v_sub_f32_e32 v48, v48, v128
.LBB0_895:
	ds_read_b128 v[124:127], v201 offset:12288
	ds_read_b128 v[128:131], v201 offset:13312
	ds_read_b128 v[136:139], v201 offset:15360
	ds_read_b128 v[140:143], v201 offset:14336
	ds_read_b128 v[148:151], v201 offset:18432
	ds_read_b128 v[152:155], v201 offset:19456
	ds_read_b128 v[204:207], v201 offset:21504
	ds_read_b128 v[208:211], v201 offset:20480
	s_waitcnt lgkmcnt(7)
	v_mfma_f32_16x16x32_bf16 v[132:135], v[124:127], v[12:15], v[44:47]
	v_exp_f32_e32 v195, v84
	v_exp_f32_e32 v194, v88
	v_exp_f32_e32 v88, v91
	v_mfma_f32_16x16x32_bf16 v[124:127], v[124:127], v[16:19], v[48:51]
	v_exp_f32_e32 v84, v81
	v_exp_f32_e32 v81, v78
	v_exp_f32_e32 v79, v79
	s_waitcnt lgkmcnt(3)
	v_mfma_f32_16x16x32_bf16 v[190:193], v[148:151], v[12:15], v[44:47]
	v_exp_f32_e32 v78, v83
	v_exp_f32_e32 v61, v61
	v_exp_f32_e32 v63, v63
	v_mfma_f32_16x16x32_bf16 v[148:151], v[148:151], v[16:19], v[48:51]
	v_exp_f32_e32 v83, v64
	v_exp_f32_e32 v64, v74
	v_exp_f32_e32 v67, v67
	v_mfma_f32_16x16x32_bf16 v[144:147], v[136:139], v[12:15], v[44:47]
	s_andn2_b64 vcc, exec, s[16:17]
	v_mfma_f32_16x16x32_bf16 v[136:139], v[136:139], v[16:19], v[48:51]
	s_waitcnt lgkmcnt(1)
	v_mfma_f32_16x16x32_bf16 v[212:215], v[204:207], v[12:15], v[44:47]
	v_mfma_f32_16x16x32_bf16 v[204:207], v[204:207], v[16:19], v[48:51]
	v_mfma_f32_16x16x32_bf16 v[132:135], v[128:131], v[4:7], v[132:135]
	v_mfma_f32_16x16x32_bf16 v[124:127], v[128:131], v[20:23], v[124:127]
	ds_read_b128 v[128:131], v201 offset:16384
	ds_read_b128 v[216:219], v201 offset:17408
	v_mfma_f32_16x16x32_bf16 v[220:223], v[152:155], v[20:23], v[148:151]
	s_nop 2
	ds_read_b128 v[148:151], v201 offset:22528
	ds_read_b128 v[224:227], v201 offset:23552
	s_waitcnt lgkmcnt(3)
	v_mfma_f32_16x16x32_bf16 v[144:147], v[128:131], v[4:7], v[144:147]
	v_mfma_f32_16x16x32_bf16 v[128:131], v[128:131], v[20:23], v[136:139]
	s_waitcnt lgkmcnt(1)
	v_mfma_f32_16x16x32_bf16 v[204:207], v[148:151], v[20:23], v[204:207]
	v_mfma_f32_16x16x32_bf16 v[136:139], v[152:155], v[4:7], v[190:193]
	v_mfma_f32_16x16x32_bf16 v[212:215], v[148:151], v[4:7], v[212:215]
	s_nop 1
	v_exp_f32_e32 v193, v85
	v_exp_f32_e32 v192, v89
	v_exp_f32_e32 v191, v86
	v_mfma_f32_16x16x32_bf16 v[148:151], v[140:143], v[8:11], v[132:135]
	v_exp_f32_e32 v190, v90
	v_exp_f32_e32 v89, v87
	v_exp_f32_e32 v87, v76
	v_mfma_f32_16x16x32_bf16 v[152:155], v[140:143], v[24:27], v[124:127]
	v_exp_f32_e32 v86, v80
	v_exp_f32_e32 v85, v77
	v_exp_f32_e32 v80, v82
	v_mfma_f32_16x16x32_bf16 v[140:143], v[216:219], v[8:11], v[144:147]
	v_exp_f32_e32 v77, v60
	v_exp_f32_e32 v76, v68
	v_exp_f32_e32 v60, v69
	v_mfma_f32_16x16x32_bf16 v[144:147], v[216:219], v[24:27], v[128:131]
	v_exp_f32_e32 v69, v62
	v_exp_f32_e32 v68, v70
	v_exp_f32_e32 v62, v71
	s_waitcnt lgkmcnt(0)
	v_mfma_f32_16x16x32_bf16 v[128:131], v[224:227], v[24:27], v[204:207]
	v_exp_f32_e32 v82, v72
	v_exp_f32_e32 v71, v65
	v_exp_f32_e32 v70, v73
	ds_read_b128 v[204:207], v200 offset:24576
	v_mfma_f32_16x16x32_bf16 v[132:135], v[208:211], v[8:11], v[136:139]
	v_exp_f32_e32 v65, v66
	v_exp_f32_e32 v66, v75
	v_cvt_pk_bf16_f32 v90, v77, v61
	v_mfma_f32_16x16x32_bf16 v[136:139], v[208:211], v[24:27], v[220:223]
	v_cvt_pk_bf16_f32 v208, v195, v193
	v_cvt_pk_bf16_f32 v209, v191, v89
	v_cvt_pk_bf16_f32 v210, v87, v85
	v_mfma_f32_16x16x32_bf16 v[124:127], v[224:227], v[8:11], v[212:215]
	v_cvt_pk_bf16_f32 v211, v81, v79
	ds_read_b128 v[216:219], v200 offset:26624
	ds_read_b128 v[220:223], v200 offset:25600
	v_cvt_pk_bf16_f32 v212, v194, v192
	v_cvt_pk_bf16_f32 v213, v190, v88
	v_cvt_pk_bf16_f32 v214, v86, v84
	v_cvt_pk_bf16_f32 v215, v80, v78
	s_waitcnt lgkmcnt(2)
	v_mfma_f32_16x16x32_bf16 v[120:123], v[204:207], v[208:211], v[120:123]
	v_cvt_pk_bf16_f32 v91, v69, v63
	v_mfma_f32_16x16x32_bf16 v[104:107], v[204:207], v[212:215], v[104:107]
	ds_read_b128 v[204:207], v200 offset:28672
	ds_read_b128 v[224:227], v200 offset:27648
	s_waitcnt lgkmcnt(3)
	v_mfma_f32_16x16x32_bf16 v[228:231], v[216:219], v[208:211], v[116:119]
	v_mfma_f32_16x16x32_bf16 v[100:103], v[216:219], v[212:215], v[100:103]
	s_nop 1
	ds_read_b128 v[116:119], v200 offset:30720
	ds_read_b128 v[216:219], v200 offset:29696
	s_waitcnt lgkmcnt(3)
	v_mfma_f32_16x16x32_bf16 v[232:235], v[204:207], v[208:211], v[112:115]
	v_mfma_f32_16x16x32_bf16 v[96:99], v[204:207], v[212:215], v[96:99]
	ds_read_b128 v[204:207], v200 offset:31744
	s_waitcnt lgkmcnt(2)
	v_mfma_f32_16x16x32_bf16 v[208:211], v[116:119], v[208:211], v[108:111]
	v_mfma_f32_16x16x32_bf16 v[72:75], v[116:119], v[212:215], v[92:95]
	v_cvt_pk_bf16_f32 v212, v76, v60
	v_cvt_pk_bf16_f32 v213, v68, v62
	v_cvt_pk_bf16_f32 v214, v82, v70
	v_cvt_pk_bf16_f32 v92, v83, v71
	v_cvt_pk_bf16_f32 v93, v65, v67
	v_cvt_pk_bf16_f32 v215, v64, v66
	s_nop 0
	v_mfma_f32_16x16x32_bf16 v[120:123], v[220:223], v[90:93], v[120:123]
	v_mfma_f32_16x16x32_bf16 v[116:119], v[220:223], v[212:215], v[104:107]
	v_max3_f32 v244, v152, v153, v154
	v_max3_f32 v245, v148, v149, v150
	v_mfma_f32_16x16x32_bf16 v[112:115], v[224:227], v[90:93], v[228:231]
	v_max3_f32 v244, v244, v155, v144
	v_max3_f32 v245, v245, v151, v140
	v_mfma_f32_16x16x32_bf16 v[108:111], v[224:227], v[212:215], v[100:103]
	v_max3_f32 v244, v244, v145, v146
	v_max3_f32 v245, v245, v141, v142
	s_waitcnt lgkmcnt(1)
	v_mfma_f32_16x16x32_bf16 v[104:107], v[216:219], v[90:93], v[232:235]
	v_max3_f32 v244, v244, v147, v136
	v_max3_f32 v245, v245, v143, v132
	v_mfma_f32_16x16x32_bf16 v[100:103], v[216:219], v[212:215], v[96:99]
	v_max3_f32 v244, v244, v137, v138
	v_max3_f32 v245, v245, v133, v134
	s_waitcnt lgkmcnt(0)
	v_mfma_f32_16x16x32_bf16 v[92:95], v[204:207], v[90:93], v[208:211]
	v_max3_f32 v244, v244, v139, v128
	v_max3_f32 v245, v245, v135, v124
	v_cndmask_b32_e64 v90, 0, 1, s[16:17]
	v_cmp_ne_u32_e64 s[14:15], 1, v90
	v_mfma_f32_16x16x32_bf16 v[96:99], v[204:207], v[212:215], v[72:75]
	v_max3_f32 v244, v244, v129, v130
	v_max3_f32 v245, v245, v125, v126
	s_cbranch_vccnz .LBB0_899
	s_waitcnt vmcnt(0)
	ds_write_b128 v197, v[52:55]
	s_and_saveexec_b64 s[16:17], s[10:11]
	ds_write_b128 v199, v[28:31]
	s_or_b64 exec, exec, s[16:17]

.LBB0_905:
	v_pk_add_f32 v[236:237], v[194:195], v[86:87]
	v_pk_add_f32 v[238:239], v[192:193], v[84:85]
	v_pk_add_f32 v[240:241], v[80:81], v[190:191]
	v_pk_add_f32 v[242:243], v[78:79], v[88:89]
	v_pk_add_f32 v[236:237], v[236:237], v[76:77]
	v_pk_add_f32 v[238:239], v[60:61], v[238:239]
	v_pk_add_f32 v[240:241], v[68:69], v[240:241]
	v_pk_add_f32 v[242:243], v[62:63], v[242:243]
	v_pk_add_f32 v[236:237], v[236:237], v[82:83]
	v_pk_add_f32 v[238:239], v[70:71], v[238:239]
	v_pk_add_f32 v[240:241], v[64:65], v[240:241]
	v_pk_add_f32 v[242:243], v[66:67], v[242:243]
	v_pk_add_f32 v[238:239], v[236:237], v[238:239]
	v_pk_add_f32 v[242:243], v[240:241], v[242:243]
	v_max_f32_e32 v60, v244, v131
	v_pk_add_f32 v[238:239], v[238:239], v[242:243]
	v_max_f32_e32 v61, v245, v127
	v_pk_add_f32 v[184:185], v[184:185], v[238:239]
	v_max_f32_e32 v62, v61, v60
	v_cmp_lt_f32_e32 vcc, s8, v62
	s_cbranch_vccz .LBB0_907
	v_and_b32_e32 v63, 64, v202
	v_xor_b32_e32 v62, 16, v202
	v_add_u32_e32 v63, 64, v63
	v_cmp_lt_i32_e32 vcc, v62, v63
	v_xor_b32_e32 v65, 32, v202
	s_nop 0
	v_cndmask_b32_e32 v62, v202, v62, vcc
	v_lshlrev_b32_e32 v62, 2, v62
	ds_bpermute_b32 v64, v62, v61
	ds_bpermute_b32 v62, v62, v60
	v_cmp_lt_i32_e32 vcc, v65, v63
	v_max_f32_e32 v61, v61, v61
	v_max_f32_e32 v60, v60, v60
	s_waitcnt lgkmcnt(1)
	v_max_f32_e32 v64, v64, v64
	v_cndmask_b32_e32 v63, v202, v65, vcc
	v_max_f32_e32 v61, v61, v64
	v_lshlrev_b32_e32 v63, 2, v63
	s_waitcnt lgkmcnt(0)
	v_max_f32_e32 v62, v62, v62
	ds_bpermute_b32 v64, v63, v61
	v_max_f32_e32 v60, v60, v62
	ds_bpermute_b32 v62, v63, v60
	s_waitcnt lgkmcnt(1)
	v_max_f32_e32 v63, v64, v64
	v_max_f32_e32 v61, v61, v63
	s_waitcnt lgkmcnt(0)
	v_max_f32_e32 v62, v62, v62
	v_max_f32_e32 v60, v60, v62
	v_cmp_lt_f32_e32 vcc, s8, v61
	s_nop 1
	v_cndmask_b32_e32 v61, 0, v61, vcc
	v_cmp_lt_f32_e32 vcc, s8, v60
	v_sub_f32_e32 v148, v148, v61
	v_sub_f32_e32 v149, v149, v61
	v_cndmask_b32_e32 v64, 0, v60, vcc
	v_exp_f32_e64 v60, -v61
	v_exp_f32_e64 v62, -v64
	v_sub_f32_e32 v150, v150, v61
	v_sub_f32_e32 v151, v151, v61
	v_sub_f32_e32 v152, v152, v64
	v_pk_mul_f32 v[118:119], v[118:119], v[62:63] op_sel_hi:[1,0]
	v_pk_mul_f32 v[116:117], v[116:117], v[62:63] op_sel_hi:[1,0]
	v_pk_mul_f32 v[110:111], v[110:111], v[62:63] op_sel_hi:[1,0]
	v_pk_mul_f32 v[108:109], v[108:109], v[62:63] op_sel_hi:[1,0]
	v_pk_mul_f32 v[102:103], v[102:103], v[62:63] op_sel_hi:[1,0]
	v_pk_mul_f32 v[100:101], v[100:101], v[62:63] op_sel_hi:[1,0]
	v_pk_mul_f32 v[98:99], v[98:99], v[62:63] op_sel_hi:[1,0]
	v_pk_mul_f32 v[96:97], v[96:97], v[62:63] op_sel_hi:[1,0]
	v_mov_b32_e32 v63, v60
	v_sub_f32_e32 v153, v153, v64
	v_sub_f32_e32 v154, v154, v64
	v_sub_f32_e32 v155, v155, v64
	v_pk_mul_f32 v[122:123], v[122:123], v[60:61] op_sel_hi:[1,0]
	v_pk_mul_f32 v[120:121], v[120:121], v[60:61] op_sel_hi:[1,0]
	v_sub_f32_e32 v140, v140, v61
	v_sub_f32_e32 v141, v141, v61
	v_sub_f32_e32 v142, v142, v61
	v_sub_f32_e32 v143, v143, v61
	v_sub_f32_e32 v144, v144, v64
	v_sub_f32_e32 v145, v145, v64
	v_sub_f32_e32 v146, v146, v64
	v_sub_f32_e32 v147, v147, v64
	v_pk_mul_f32 v[114:115], v[114:115], v[60:61] op_sel_hi:[1,0]
	v_pk_mul_f32 v[112:113], v[112:113], v[60:61] op_sel_hi:[1,0]
	v_sub_f32_e32 v132, v132, v61
	v_sub_f32_e32 v133, v133, v61
	v_sub_f32_e32 v134, v134, v61
	v_sub_f32_e32 v135, v135, v61
	v_sub_f32_e32 v136, v136, v64
	v_sub_f32_e32 v137, v137, v64
	v_sub_f32_e32 v138, v138, v64
	v_sub_f32_e32 v139, v139, v64
	v_pk_mul_f32 v[106:107], v[106:107], v[60:61] op_sel_hi:[1,0]
	v_pk_mul_f32 v[104:105], v[104:105], v[60:61] op_sel_hi:[1,0]
	v_sub_f32_e32 v124, v124, v61
	v_sub_f32_e32 v125, v125, v61
	v_sub_f32_e32 v126, v126, v61
	v_sub_f32_e32 v127, v127, v61
	v_sub_f32_e32 v128, v128, v64
	v_sub_f32_e32 v129, v129, v64
	v_sub_f32_e32 v130, v130, v64
	v_sub_f32_e32 v131, v131, v64
	v_pk_mul_f32 v[94:95], v[94:95], v[60:61] op_sel_hi:[1,0]
	v_pk_mul_f32 v[92:93], v[92:93], v[60:61] op_sel_hi:[1,0]
	v_pk_mul_f32 v[184:185], v[184:185], v[62:63]
	v_sub_f32_e32 v47, v47, v61
	v_sub_f32_e32 v46, v46, v61
	v_sub_f32_e32 v45, v45, v61
	v_sub_f32_e32 v44, v44, v61
	v_sub_f32_e32 v51, v51, v64
	v_sub_f32_e32 v50, v50, v64
	v_sub_f32_e32 v49, v49, v64
	v_sub_f32_e32 v48, v48, v64
.LBB0_907:
	ds_read_b128 v[60:63], v201
	ds_read_b128 v[64:67], v201 offset:1024
	ds_read_b128 v[72:75], v201 offset:3072
	ds_read_b128 v[76:79], v201 offset:2048
	ds_read_b128 v[84:87], v201 offset:6144
	ds_read_b128 v[88:91], v201 offset:7168
	ds_read_b128 v[190:193], v201 offset:9216
	ds_read_b128 v[204:207], v201 offset:8192
	s_waitcnt lgkmcnt(7)
	v_mfma_f32_16x16x32_bf16 v[68:71], v[60:63], v[12:15], v[44:47]
	v_exp_f32_e32 v149, v149
	v_exp_f32_e32 v151, v151
	v_exp_f32_e32 v143, v143
	v_mfma_f32_16x16x32_bf16 v[60:63], v[60:63], v[16:19], v[48:51]
	v_exp_f32_e32 v133, v133
	v_exp_f32_e32 v135, v135
	v_exp_f32_e32 v127, v127
	s_waitcnt lgkmcnt(3)
	v_mfma_f32_16x16x32_bf16 v[186:189], v[84:87], v[12:15], v[44:47]
	s_and_b64 vcc, exec, s[16:17]
	v_mfma_f32_16x16x32_bf16 v[84:87], v[84:87], v[16:19], v[48:51]
	v_mfma_f32_16x16x32_bf16 v[80:83], v[72:75], v[12:15], v[44:47]
	v_mfma_f32_16x16x32_bf16 v[72:75], v[72:75], v[16:19], v[48:51]
	s_waitcnt lgkmcnt(1)
	v_mfma_f32_16x16x32_bf16 v[208:211], v[190:193], v[12:15], v[44:47]
	v_mfma_f32_16x16x32_bf16 v[190:193], v[190:193], v[16:19], v[48:51]
	v_mfma_f32_16x16x32_bf16 v[68:71], v[64:67], v[4:7], v[68:71]
	v_mfma_f32_16x16x32_bf16 v[60:63], v[64:67], v[20:23], v[60:63]
	ds_read_b128 v[64:67], v201 offset:4096
	ds_read_b128 v[212:215], v201 offset:5120
	v_mfma_f32_16x16x32_bf16 v[216:219], v[88:91], v[20:23], v[84:87]
	s_nop 2
	ds_read_b128 v[84:87], v201 offset:10240
	ds_read_b128 v[220:223], v201 offset:11264
	s_waitcnt lgkmcnt(3)
	v_mfma_f32_16x16x32_bf16 v[80:83], v[64:67], v[4:7], v[80:83]
	v_mfma_f32_16x16x32_bf16 v[64:67], v[64:67], v[20:23], v[72:75]
	v_mfma_f32_16x16x32_bf16 v[72:75], v[88:91], v[4:7], v[186:189]
	s_waitcnt lgkmcnt(1)
	v_mfma_f32_16x16x32_bf16 v[188:191], v[84:87], v[20:23], v[190:193]
	s_nop 0
	v_exp_f32_e32 v187, v148
	v_exp_f32_e32 v186, v152
	v_exp_f32_e32 v148, v153
	v_mfma_f32_16x16x32_bf16 v[88:91], v[76:79], v[24:27], v[60:63]
	v_exp_f32_e32 v153, v150
	v_exp_f32_e32 v152, v154
	v_exp_f32_e32 v150, v155
	v_mfma_f32_16x16x32_bf16 v[60:63], v[204:207], v[8:11], v[72:75]
	v_exp_f32_e32 v155, v141
	v_exp_f32_e32 v154, v145
	v_exp_f32_e32 v145, v142
	s_waitcnt lgkmcnt(0)
	v_mfma_f32_16x16x32_bf16 v[72:75], v[220:223], v[24:27], v[188:191]
	v_exp_f32_e32 v142, v147
	v_exp_f32_e32 v141, v132
	v_exp_f32_e32 v132, v137
	ds_read_b128 v[190:193], v200 offset:32768
	v_mfma_f32_16x16x32_bf16 v[208:211], v[84:87], v[4:7], v[208:211]
	v_exp_f32_e32 v189, v140
	v_exp_f32_e32 v188, v144
	v_exp_f32_e32 v144, v146
	v_mfma_f32_16x16x32_bf16 v[84:87], v[76:79], v[8:11], v[68:71]
	v_exp_f32_e32 v140, v136
	v_exp_f32_e32 v137, v134
	v_exp_f32_e32 v136, v138
	v_mfma_f32_16x16x32_bf16 v[76:79], v[212:215], v[8:11], v[80:83]
	v_exp_f32_e32 v134, v139
	v_exp_f32_e32 v139, v124
	v_exp_f32_e32 v138, v128
	v_mfma_f32_16x16x32_bf16 v[80:83], v[212:215], v[24:27], v[64:67]
	v_exp_f32_e32 v147, v125
	v_exp_f32_e32 v146, v129
	v_exp_f32_e32 v125, v126
	v_mfma_f32_16x16x32_bf16 v[68:71], v[204:207], v[24:27], v[216:219]
	ds_read_b128 v[212:215], v200 offset:34816
	s_nop 1
	ds_read_b128 v[216:219], v200 offset:33792
	v_cvt_pk_bf16_f32 v204, v187, v149
	v_cvt_pk_bf16_f32 v205, v153, v151
	v_mfma_f32_16x16x32_bf16 v[64:67], v[220:223], v[8:11], v[208:211]
	v_cvt_pk_bf16_f32 v206, v189, v155
	v_cvt_pk_bf16_f32 v207, v145, v143
	v_exp_f32_e32 v124, v130
	v_cvt_pk_bf16_f32 v208, v186, v148
	v_cvt_pk_bf16_f32 v209, v152, v150
	v_cvt_pk_bf16_f32 v210, v188, v154
	v_cvt_pk_bf16_f32 v211, v144, v142
	s_waitcnt lgkmcnt(2)
	v_mfma_f32_16x16x32_bf16 v[120:123], v[190:193], v[204:207], v[120:123]
	v_exp_f32_e32 v126, v131
	v_mfma_f32_16x16x32_bf16 v[116:119], v[190:193], v[208:211], v[116:119]
	ds_read_b128 v[190:193], v200 offset:36864
	ds_read_b128 v[220:223], v200 offset:35840
	s_waitcnt lgkmcnt(3)
	v_mfma_f32_16x16x32_bf16 v[112:115], v[212:215], v[204:207], v[112:115]
	v_mfma_f32_16x16x32_bf16 v[108:111], v[212:215], v[208:211], v[108:111]
	ds_read_b128 v[212:215], v200 offset:38912
	ds_read_b128 v[224:227], v200 offset:37888
	ds_read_b128 v[232:235], v200 offset:39936
	s_waitcnt lgkmcnt(4)
	v_mfma_f32_16x16x32_bf16 v[228:231], v[190:193], v[204:207], v[104:107]
	v_mfma_f32_16x16x32_bf16 v[190:193], v[190:193], v[208:211], v[100:103]
	s_waitcnt lgkmcnt(2)
	v_mfma_f32_16x16x32_bf16 v[92:95], v[212:215], v[204:207], v[92:95]
	v_cvt_pk_bf16_f32 v204, v141, v133
	v_cvt_pk_bf16_f32 v205, v137, v135
	v_cvt_pk_bf16_f32 v206, v139, v147
	v_mfma_f32_16x16x32_bf16 v[128:131], v[212:215], v[208:211], v[96:99]
	v_cvt_pk_bf16_f32 v207, v125, v127
	v_cvt_pk_bf16_f32 v208, v140, v132
	v_cvt_pk_bf16_f32 v209, v136, v134
	v_cvt_pk_bf16_f32 v210, v138, v146
	v_cvt_pk_bf16_f32 v211, v124, v126
	v_mfma_f32_16x16x32_bf16 v[120:123], v[216:219], v[204:207], v[120:123]
	s_nop 0
	v_mfma_f32_16x16x32_bf16 v[104:107], v[216:219], v[208:211], v[116:119]
	v_max3_f32 v246, v88, v89, v90
	v_max3_f32 v247, v84, v85, v86
	v_mfma_f32_16x16x32_bf16 v[116:119], v[220:223], v[204:207], v[112:115]
	v_max3_f32 v246, v246, v91, v80
	v_max3_f32 v247, v247, v87, v76
	v_mfma_f32_16x16x32_bf16 v[100:103], v[220:223], v[208:211], v[108:111]
	v_max3_f32 v246, v246, v81, v82
	v_max3_f32 v247, v247, v77, v78
	s_waitcnt lgkmcnt(1)
	v_mfma_f32_16x16x32_bf16 v[112:115], v[224:227], v[204:207], v[228:231]
	v_max3_f32 v246, v246, v83, v68
	v_max3_f32 v247, v247, v79, v60
	v_mfma_f32_16x16x32_bf16 v[96:99], v[224:227], v[208:211], v[190:193]
	v_max3_f32 v246, v246, v69, v70
	v_max3_f32 v247, v247, v61, v62
	s_waitcnt lgkmcnt(0)
	v_mfma_f32_16x16x32_bf16 v[108:111], v[232:235], v[204:207], v[92:95]
	v_max3_f32 v246, v246, v71, v72
	v_max3_f32 v247, v247, v63, v64
	v_mfma_f32_16x16x32_bf16 v[92:95], v[232:235], v[208:211], v[128:131]
	v_max3_f32 v246, v246, v73, v74
	v_max3_f32 v247, v247, v65, v66
	s_cbranch_vccnz .LBB0_911
	ds_write_b128 v197, v[32:35] offset:12288
	s_and_saveexec_b64 s[16:17], s[10:11]
	ds_write_b128 v199, v[36:39] offset:12288
	s_or_b64 exec, exec, s[16:17]
